# attention gate (GB) prefetch widened to 4x dwordx4 loads with permlane16_swap un-swap
# speedup vs baseline: 1.0342x; 1.0029x over previous
; __device__ __forceinline__ unsigned cvt_pk_bf16(float lo, float hi) { unsigned r; asm volatile("v_cvt_pk_bf16_f32 %0, %1, %2" : "=v"(r) : "v"(lo), "v"(hi)); return r; }
; __device__ __forceinline__ float bflo(unsigned w) { return __uint_as_float(w << 16); }
; __device__ __forceinline__ float bfhi(unsigned w) { return __uint_as_float(w & 0xffff0000u); }
; __device__ __forceinline__ void attn_unit(LAS unsigned char* lds, const bf16_t* Qm, const bf16_t* Km, const bf16_t* VT, const bf16_t* GBm, bf16_t* YB, int b, int hp, int qb) {
;     ...
;     {
;         const size_t off = (rowbase + qw + fr) * 1024 + h * 128 + fq * 4;
; #pragma unroll
;         for (int db = 0; db < 8; ++db) {
;             const u32x2 gw = *(const u32x2*)(GBm + off + db * 16);
;             u32x2 w; w.x = cvt_pk_bf16(o[db][0] * bflo(gw.x), o[db][1] * bfhi(gw.x)); w.y = cvt_pk_bf16(o[db][2] * bflo(gw.y), o[db][3] * bfhi(gw.y));
;             *(u32x2*)(YB + off + db * 16) = w;
;         }
;     }
.LBB0_514:
	v_lshl_add_u64 v[0:1], v[82:83], 0, v[84:85]
	v_lshl_or_b32 v0, v106, 2, v0
	v_lshlrev_b64 v[0:1], 1, v[0:1]
	v_lshl_add_u64 v[0:1], s[20:21], 0, v[0:1]
	v_and_b32_e32 v2, 1, v106
	v_mul_u32_u24_e32 v2, 24, v2
	v_mov_b32_e32 v3, 0
	v_lshl_add_u64 v[0:1], v[2:3], 0, v[0:1]
	s_add_i32 s39, s39, s34
	s_cmpk_gt_i32 s39, 0x7ff
	s_waitcnt vmcnt(0)
	v_permlane16_swap_b32_e32 v172, v174
	v_permlane16_swap_b32_e32 v173, v175
	v_permlane16_swap_b32_e32 v176, v178
	v_permlane16_swap_b32_e32 v177, v179
	v_permlane16_swap_b32_e32 v180, v182
	v_permlane16_swap_b32_e32 v181, v183
	v_permlane16_swap_b32_e32 v184, v186
	v_permlane16_swap_b32_e32 v185, v187
	v_lshlrev_b32_e32 v6, 16, v172
	v_and_b32_e32 v4, 0xffff0000, v172
	v_lshlrev_b32_e32 v7, 16, v173
	v_and_b32_e32 v5, 0xffff0000, v173
	v_mul_f32_e32 v6, v60, v6
	v_mul_f32_e32 v4, v61, v4
	v_mul_f32_e32 v7, v62, v7
	v_mul_f32_e32 v5, v63, v5
	v_cvt_pk_bf16_f32 v208, v6, v4
	v_cvt_pk_bf16_f32 v209, v7, v5
	v_lshlrev_b32_e32 v10, 16, v174
	v_and_b32_e32 v8, 0xffff0000, v174
	v_lshlrev_b32_e32 v11, 16, v175
	v_and_b32_e32 v9, 0xffff0000, v175
	v_mul_f32_e32 v10, v72, v10
	v_mul_f32_e32 v8, v73, v8
	v_mul_f32_e32 v11, v74, v11
	v_mul_f32_e32 v9, v75, v9
	v_cvt_pk_bf16_f32 v210, v10, v8
	v_cvt_pk_bf16_f32 v211, v11, v9
	v_lshlrev_b32_e32 v6, 16, v176
	v_and_b32_e32 v4, 0xffff0000, v176
	v_lshlrev_b32_e32 v7, 16, v177
	v_and_b32_e32 v5, 0xffff0000, v177
	v_mul_f32_e32 v6, v56, v6
	v_mul_f32_e32 v4, v57, v4
	v_mul_f32_e32 v7, v58, v7
	v_mul_f32_e32 v5, v59, v5
	v_cvt_pk_bf16_f32 v212, v6, v4
	v_cvt_pk_bf16_f32 v213, v7, v5
	v_lshlrev_b32_e32 v10, 16, v178
	v_and_b32_e32 v8, 0xffff0000, v178
	v_lshlrev_b32_e32 v11, 16, v179
	v_and_b32_e32 v9, 0xffff0000, v179
	v_mul_f32_e32 v10, v44, v10
	v_mul_f32_e32 v8, v45, v8
	v_mul_f32_e32 v11, v46, v11
	v_mul_f32_e32 v9, v47, v9
	v_cvt_pk_bf16_f32 v214, v10, v8
	v_cvt_pk_bf16_f32 v215, v11, v9
	v_lshlrev_b32_e32 v6, 16, v180
	v_and_b32_e32 v4, 0xffff0000, v180
	v_lshlrev_b32_e32 v7, 16, v181
	v_and_b32_e32 v5, 0xffff0000, v181
	v_mul_f32_e32 v6, v32, v6
	v_mul_f32_e32 v4, v33, v4
	v_mul_f32_e32 v7, v34, v7
	v_mul_f32_e32 v5, v35, v5
	v_cvt_pk_bf16_f32 v240, v6, v4
	v_cvt_pk_bf16_f32 v241, v7, v5
	v_lshlrev_b32_e32 v10, 16, v182
	v_and_b32_e32 v8, 0xffff0000, v182
	v_lshlrev_b32_e32 v11, 16, v183
	v_and_b32_e32 v9, 0xffff0000, v183
	v_mul_f32_e32 v10, v24, v10
	v_mul_f32_e32 v8, v25, v8
	v_mul_f32_e32 v11, v26, v11
	v_mul_f32_e32 v9, v27, v9
	v_cvt_pk_bf16_f32 v242, v10, v8
	v_cvt_pk_bf16_f32 v243, v11, v9
	v_lshlrev_b32_e32 v6, 16, v184
	v_and_b32_e32 v4, 0xffff0000, v184
	v_lshlrev_b32_e32 v7, 16, v185
	v_and_b32_e32 v5, 0xffff0000, v185
	v_mul_f32_e32 v6, v20, v6
	v_mul_f32_e32 v4, v21, v4
	v_mul_f32_e32 v7, v22, v7
	v_mul_f32_e32 v5, v23, v5
	v_cvt_pk_bf16_f32 v244, v6, v4
	v_cvt_pk_bf16_f32 v245, v7, v5
	v_lshlrev_b32_e32 v10, 16, v186
	v_and_b32_e32 v8, 0xffff0000, v186
	v_lshlrev_b32_e32 v11, 16, v187
	v_and_b32_e32 v9, 0xffff0000, v187
	v_mul_f32_e32 v10, v16, v10
	v_mul_f32_e32 v8, v17, v8
	v_mul_f32_e32 v11, v18, v11
	v_mul_f32_e32 v9, v19, v9
	v_cvt_pk_bf16_f32 v246, v10, v8
	v_cvt_pk_bf16_f32 v247, v11, v9
	s_nop 1
	v_permlane16_swap_b32_e32 v208, v210
	v_permlane16_swap_b32_e32 v209, v211
	v_permlane16_swap_b32_e32 v212, v214
	v_permlane16_swap_b32_e32 v213, v215
	v_permlane16_swap_b32_e32 v240, v242
	v_permlane16_swap_b32_e32 v241, v243
	v_permlane16_swap_b32_e32 v244, v246
	v_permlane16_swap_b32_e32 v245, v247
	global_store_dwordx4 v[0:1], v[208:211], off
	global_store_dwordx4 v[0:1], v[212:215], off offset:64
	global_store_dwordx4 v[0:1], v[240:243], off offset:128
	global_store_dwordx4 v[0:1], v[244:247], off offset:192
	s_barrier
	s_cbranch_scc1 .LBB0_524
; #define LAS __attribute__((address_space(3)))
; #define ATT_LOAD(kbi) do { const int k0_ = (kbi) * 64; _Pragma("unroll") for (int i_ = 0; i_ < 4; ++i_) { const int ci = (tid + 512 * i_) & 1023, hh_ = 2 * hp + (i_ >> 1); \
;         pk[i_] = *(const u32x4*)(Km + (rowbase + k0_ + (ci >> 4)) * 1024 + hh_ * 128 + (ci & 15) * 8); \
;         pv[i_] = *(const u32x4*)(VT + (size_t)(hh_ * 128 + (ci >> 3)) * T + rowbase + k0_ + (ci & 7) * 8); } } while (0)
; __device__ __forceinline__ void attn_unit(LAS unsigned char* lds, const bf16_t* Qm, const bf16_t* Km, const bf16_t* VT, const bf16_t* GBm, bf16_t* YB, int b, int hp, int qb) {
;     ...
;     const int tid = tidl_, wave = tid >> 6, lane = tid & 63, fr = lane & 15, fq = lane >> 4;
;     const int hsel = wave >> 2, h = 2 * hp + hsel;
;     const int q0 = qb * 64, qw = q0 + (hsel ? 3 - (wave & 3) : (wave & 3)) * 16;
;     const size_t rowbase = (size_t)b * SEQ;
;     LAS unsigned char* KL = lds + hsel * 35840;
;     LAS unsigned char* VL = KL + 17408;
;     volatile LAS int* FL = (volatile LAS int*)(lds + 71680);
;     bf16x8 qf[4];
;     { const bf16_t* qp = Qm + (rowbase + qw + fr) * 1024 + h * 128 + fq * 8;
; #pragma unroll
;       for (int ks = 0; ks < 4; ++ks) qf[ks] = *(const bf16x8*)(qp + ks * 32); }
;     f32x4 o[8];
; #pragma unroll
;     for (int d = 0; d < 8; ++d) o[d] = (f32x4){0.f, 0.f, 0.f, 0.f};
;     float Rs = 1.f;
;     int kb = q0 >> 6;
;     u32x4 pk[4], pv[4];
;     ...
;     ATT_LOAD(kb);
;     ...
;     {
;         const size_t off = (rowbase + qw + fr) * 1024 + h * 128 + fq * 4;
; #pragma unroll
;         for (int db = 0; db < 8; ++db) {
;             const u32x2 gw = *(const u32x2*)(GBm + off + db * 16);
.LBB0_515:
	v_mov_b32_e32 v32, v226
	s_ashr_i32 s0, s39, 4
	s_sub_i32 s0, 0x7f, s0
	v_ashrrev_i32_e32 v33, 6, v32
	v_bitop3_b32 v0, v33, 3, v33 bitop3:0xc
	v_cmp_gt_u32_e32 vcc, s6, v32
	s_lshl_b32 s1, s39, 11
	s_lshl_b32 s56, s0, 6
	v_cndmask_b32_e32 v0, v0, v33, vcc
	s_and_b32 s60, s1, 0x6000
	s_lshl_b32 s1, s39, 8
	v_lshl_add_u32 v44, v0, 4, s56
	s_and_b32 s8, s1, 0x300
	s_and_b32 s61, s0, 0x3ffffff
	s_add_i32 s9, s56, s60
	s_lshl_b32 s0, s60, 1
	v_and_b32_e32 v34, 15, v32
	v_add_u32_e32 v0, s60, v44
	s_add_u32 s0, s26, s0
	v_bitop3_b32 v36, v32, s7, v104 bitop3:0x6c
	v_ashrrev_i32_e32 v35, 8, v32
	v_or_b32_e32 v80, v0, v34
	s_addc_u32 s1, s27, 0
	s_lshl_b64 s[4:5], s[56:57], 1
	v_lshrrev_b32_e32 v88, 4, v36
	v_lshlrev_b64 v[0:1], 11, v[80:81]
	v_lshl_add_u32 v84, v35, 7, s8
	s_add_u32 s4, s0, s4
	v_lshlrev_b32_e32 v22, 4, v32
	v_bfe_u32 v86, v32, 4, 6
	v_bfe_u32 v45, v32, 3, 7
	v_or_b32_e32 v26, s9, v88
	v_mov_b32_e32 v27, v81
	v_lshl_add_u64 v[0:1], s[46:47], 0, v[0:1]
	v_ashrrev_i32_e32 v85, 31, v84
	s_addc_u32 s5, s1, s5
	v_and_b32_e32 v16, 0x70, v22
	v_mov_b32_e32 v17, v81
	v_or_b32_e32 v20, s9, v86
	v_mov_b32_e32 v21, v81
	v_or_b32_e32 v46, s8, v45
	v_lshlrev_b64 v[26:27], 11, v[26:27]
	v_lshlrev_b64 v[82:83], 10, v[80:81]
	v_lshl_add_u64 v[0:1], v[84:85], 1, v[0:1]
	v_and_b32_e32 v80, 48, v32
	v_lshl_add_u64 v[18:19], s[4:5], 0, v[16:17]
	v_lshlrev_b64 v[20:21], 11, v[20:21]
	s_lshl_b32 s12, s8, 1
	s_mov_b32 s13, s57
	v_lshlrev_b32_e32 v24, 16, v46
	v_mov_b32_e32 v25, v81
	v_lshl_add_u64 v[26:27], s[44:45], 0, v[26:27]
	v_lshrrev_b32_e32 v47, 3, v36
	v_lshl_add_u64 v[12:13], v[0:1], 0, v[80:81]
	v_lshl_add_u64 v[20:21], s[44:45], 0, v[20:21]
	v_and_b32_e32 v22, 0xf0, v22
	v_mov_b32_e32 v23, v81
	v_lshl_add_u64 v[24:25], v[18:19], 0, v[24:25]
	v_lshl_add_u64 v[26:27], v[26:27], 0, s[12:13]
	v_or_b32_e32 v56, s8, v47
	v_lshl_add_u64 v[188:189], v[82:83], 0, v[84:85]
	v_bfe_u32 v190, v226, 4, 2
	v_lshl_or_b32 v188, v190, 2, v188
	v_lshlrev_b64 v[188:189], 1, v[188:189]
	v_lshl_add_u64 v[188:189], s[30:31], 0, v[188:189]
	v_and_b32_e32 v190, 1, v190
	v_mul_u32_u24_e32 v190, 24, v190
	v_mov_b32_e32 v191, 0
	v_lshl_add_u64 v[188:189], v[190:191], 0, v[188:189]
	global_load_dwordx4 v[172:175], v[188:189], off
	global_load_dwordx4 v[176:179], v[188:189], off offset:64
	global_load_dwordx4 v[180:183], v[188:189], off offset:128
	global_load_dwordx4 v[184:187], v[188:189], off offset:192
	global_load_dwordx4 v[0:3], v[12:13], off
	global_load_dwordx4 v[4:7], v[12:13], off offset:64
	global_load_dwordx4 v[8:11], v[12:13], off offset:128
	s_nop 0
	global_load_dwordx4 v[12:15], v[12:13], off offset:192
	v_lshl_add_u64 v[20:21], v[20:21], 0, s[12:13]
	v_lshl_add_u64 v[26:27], v[26:27], 0, v[22:23]
	v_lshrrev_b32_e32 v196, 3, v226
	v_and_b32_e32 v197, 7, v226
	v_lshlrev_b32_e32 v197, 4, v197
	v_add_u32_e32 v198, s8, v196
	v_lshlrev_b32_e32 v198, 9, v198
	v_or_b32_e32 v198, v198, v197
	v_mov_b32_e32 v199, 0
	s_mov_b32 s66, 0x8000
	s_mov_b32 s67, 0
	v_lshl_add_u64 v[216:217], v[198:199], 0, s[26:27]
	v_lshl_add_u64 v[218:219], v[216:217], 0, s[66:67]
	v_lshl_add_u64 v[220:221], v[218:219], 0, s[66:67]
	v_lshl_add_u64 v[222:223], v[220:221], 0, s[66:67]
	s_add_i32 s68, s60, s56
	s_lshr_b32 s66, s68, 8
	s_lshl_b32 s66, s66, 19
	s_bfe_u32 s67, s68, 0x20006
	s_lshl_b32 s67, s67, 7
	s_or_b32 s68, s66, s67
	s_mov_b32 s69, 0
	v_lshl_add_u64 v[200:201], v[216:217], 0, s[68:69]
	v_lshl_add_u64 v[202:203], v[218:219], 0, s[68:69]
	v_lshl_add_u64 v[204:205], v[220:221], 0, s[68:69]
	v_lshl_add_u64 v[206:207], v[222:223], 0, s[68:69]
	global_load_dwordx4 v[28:31], v[200:201], off
	global_load_dwordx4 v[40:43], v[26:27], off
	v_lshlrev_b32_e32 v24, 16, v56
	v_mov_b32_e32 v25, v81
	s_or_b32 s58, s8, 0x80
	v_lshl_add_u64 v[20:21], v[20:21], 0, v[22:23]
	v_lshl_add_u64 v[24:25], v[18:19], 0, v[24:25]
	v_or_b32_e32 v57, s58, v45
	global_load_dwordx4 v[36:39], v[20:21], off
	global_load_dwordx4 v[48:51], v[20:21], off offset:256
	v_lshlrev_b32_e32 v20, 16, v57
	v_mov_b32_e32 v21, v81
	global_load_dwordx4 v[52:55], v[202:203], off
	global_load_dwordx4 v[64:67], v[26:27], off offset:256
	v_or_b32_e32 v26, s58, v47
	v_lshl_add_u64 v[20:21], v[18:19], 0, v[20:21]
	v_lshlrev_b32_e32 v24, 16, v26
	v_mov_b32_e32 v25, v81
	v_lshl_add_u64 v[18:19], v[18:19], 0, v[24:25]
	global_load_dwordx4 v[68:71], v[204:205], off
	global_load_dwordx4 v[76:79], v[206:207], off
	v_lshl_add_u64 v[90:91], s[0:1], 0, v[16:17]
	v_lshlrev_b32_e32 v17, 1, v32
	v_and_b32_e32 v21, 3, v32
	v_and_or_b32 v17, v17, 24, v21
	v_add_u32_e32 v21, 16, v32
	v_mul_i32_i24_e32 v19, 0x8c00, v35
	v_and_b32_e32 v21, 63, v21
	v_add_u32_e32 v25, 48, v32
	v_mad_u32_u24 v35, v45, s38, 0
	v_mad_u32_u24 v45, v47, s38, 0
	s_add_u32 s12, s44, s12
	v_and_b32_e32 v25, 63, v25
	s_addc_u32 s13, s45, 0
	v_add_u32_e32 v113, v35, v16
	v_add_u32_e32 v115, v45, v16
	v_or_b32_e32 v16, v105, v21
	v_and_b32_e32 v107, 63, v32
	v_bfe_u32 v106, v32, 4, 2
	v_lshlrev_b32_e32 v18, 15, v46
	v_lshlrev_b32_e32 v20, 15, v56
	v_lshlrev_b32_e32 v24, 15, v57
	v_lshlrev_b32_e32 v26, 15, v26
	v_or_b32_e32 v109, 15, v44
	v_lshl_add_u32 v110, v33, 2, s28
	v_add3_u32 v19, 0, v19, v80
	v_or_b32_e32 v111, v44, v34
	v_mad_u32_u24 v27, v86, s29, 0
	v_mad_u32_u24 v44, v88, s29, 0
	v_lshl_add_u64 v[92:93], s[12:13], 0, v[22:23]
	v_lshl_add_u64 v[32:33], s[44:45], 0, v[22:23]
	v_mul_u32_u24_e32 v17, 0x110, v17
	v_mul_u32_u24_e32 v23, 0x90, v34
	s_lshl_b32 s12, s58, 1
	s_mov_b32 s13, s57
	v_mov_b32_e32 v60, v81
	v_mov_b32_e32 v61, v81
	v_mov_b32_e32 v62, v81
	v_mov_b32_e32 v63, v81
	v_lshlrev_b32_e32 v118, 2, v16
	v_or_b32_e32 v16, v105, v25
	v_lshl_add_u64 v[94:95], v[32:33], 0, s[12:13]
	v_add_u32_e32 v112, v27, v22
	v_add_u32_e32 v114, v44, v22
	v_lshlrev_b32_e32 v80, 1, v18
	v_lshlrev_b32_e32 v98, 1, v20
	v_lshlrev_b32_e32 v100, 1, v24
	v_lshlrev_b32_e32 v102, 1, v26
	v_add_u32_e32 v116, v19, v17
	v_add_u32_e32 v117, v19, v23
	v_lshlrev_b32_e32 v119, 2, v16
	v_mov_b64_e32 v[74:75], v[62:63]
	v_mov_b64_e32 v[56:57], v[60:61]
	v_mov_b64_e32 v[44:45], v[60:61]
	v_mov_b64_e32 v[32:33], v[60:61]
	v_mov_b64_e32 v[24:25], v[60:61]
	v_mov_b64_e32 v[20:21], v[60:61]
	v_mov_b64_e32 v[16:17], v[60:61]
	v_lshlrev_b32_e32 v108, 3, v106
	v_mov_b32_e32 v87, v81
	v_mov_b32_e32 v89, v81
	v_cmp_eq_u32_e64 s[0:1], 3, v106
	v_cmp_gt_u32_e64 s[10:11], 32, v107
	v_cmp_gt_u32_e64 s[4:5], 16, v107
	v_cmp_eq_u32_e64 s[8:9], 0, v107
	s_lshl_b32 s62, s61, 3
	s_sub_i32 s56, s56, 64
	v_mov_b32_e32 v96, 1.0
	s_mov_b32 s63, s57
	v_mov_b64_e32 v[72:73], v[60:61]
	v_mov_b64_e32 v[58:59], v[62:63]
	v_mov_b64_e32 v[46:47], v[62:63]
	v_mov_b64_e32 v[34:35], v[62:63]
	v_mov_b64_e32 v[26:27], v[62:63]
	v_mov_b64_e32 v[22:23], v[62:63]
	v_mov_b64_e32 v[18:19], v[62:63]
	s_branch .LBB0_517
